# retention state scan (r2): the 15 per-chunk state loads issued up front (was a 16-step load-wait-store ladder per element), one code path for both directions
# speedup vs baseline: 1.0008x; 1.0008x over previous
.LBB0_1115:
	v_lshrrev_b32_e32 v3, 9, v1
	v_readlane_b32 s0, v251, 2
	v_and_b32_e32 v3, 8, v3
	v_readlane_b32 s1, v251, 3
	v_ashrrev_i32_e32 v2, 13, v1
	v_lshlrev_b32_e32 v6, 2, v2
	v_and_b32_e32 v130, 28, v6
	s_mov_b32 s3, 0xbfb8aa3b
	v_and_b32_e32 v0, 0xfff, v1
	global_load_dwordx2 v[4:5], v3, s[0:1] offset:144
	s_waitcnt vmcnt(0)
	v_lshl_add_u64 v[4:5], v[4:5], 0, v[130:131]
	global_load_dword v4, v[4:5], off
	s_waitcnt vmcnt(0)
	v_mul_f32_e32 v5, 0xbfb8aa3b, v4
	v_fma_f32 v6, v4, s3, -v5
	v_rndne_f32_e32 v7, v5
	v_fmac_f32_e32 v6, 0xb2a5705f, v4
	v_sub_f32_e32 v5, v5, v7
	v_add_f32_e32 v5, v5, v6
	v_exp_f32_e32 v5, v5
	v_cvt_i32_f32_e32 v6, v7
	s_mov_b32 s3, 0x42ce8ed0
	v_cmp_nlt_f32_e32 vcc, s3, v4
	s_mov_b32 s3, 0xc2b17218
	v_ldexp_f32 v5, v5, v6
	v_cndmask_b32_e32 v5, 0, v5, vcc
	v_cmp_ngt_f32_e32 vcc, s3, v4
	s_mov_b32 s3, 0x3f2aaaab
	s_nop 0
	v_cndmask_b32_e32 v6, v172, v5, vcc
	v_add_f32_e32 v7, 1.0, v6
	v_add_f32_e32 v4, -1.0, v7
	v_sub_f32_e32 v5, v4, v7
	v_add_f32_e32 v5, 1.0, v5
	v_sub_f32_e32 v4, v6, v4
	v_add_f32_e32 v8, v4, v5
	v_frexp_mant_f32_e32 v4, v7
	v_cmp_gt_f32_e32 vcc, s3, v4
	v_cvt_f64_f32_e32 v[4:5], v7
	v_frexp_exp_i32_f64_e32 v4, v[4:5]
	v_subbrev_co_u32_e32 v4, vcc, 0, v4, vcc
	v_sub_u32_e32 v5, 0, v4
	v_ldexp_f32 v7, v7, v5
	v_ldexp_f32 v5, v8, v5
	v_add_f32_e32 v8, -1.0, v7
	v_add_f32_e32 v9, 1.0, v8
	v_sub_f32_e32 v9, v7, v9
	v_add_f32_e32 v9, v5, v9
	v_add_f32_e32 v10, v8, v9
	v_sub_f32_e32 v8, v8, v10
	v_add_f32_e32 v8, v9, v8
	v_add_f32_e32 v9, 1.0, v7
	v_add_f32_e32 v11, -1.0, v9
	v_sub_f32_e32 v7, v7, v11
	v_add_f32_e32 v5, v5, v7
	v_add_f32_e32 v7, v9, v5
	v_sub_f32_e32 v9, v9, v7
	v_add_f32_e32 v5, v5, v9
	v_rcp_f32_e32 v9, v7
	v_cvt_f32_i32_e32 v4, v4
	s_mov_b32 s3, 0x3f317218
	v_mul_f32_e32 v11, v10, v9
	v_mul_f32_e32 v12, v7, v11
	v_fma_f32 v13, v11, v7, -v12
	v_fmac_f32_e32 v13, v11, v5
	v_add_f32_e32 v14, v12, v13
	v_sub_f32_e32 v15, v10, v14
	v_sub_f32_e32 v10, v10, v15
	v_sub_f32_e32 v12, v14, v12
	v_sub_f32_e32 v10, v10, v14
	v_add_f32_e32 v8, v8, v10
	v_sub_f32_e32 v10, v12, v13
	v_add_f32_e32 v8, v10, v8
	v_add_f32_e32 v10, v15, v8
	v_mul_f32_e32 v12, v9, v10
	v_mul_f32_e32 v13, v7, v12
	v_fma_f32 v7, v12, v7, -v13
	v_fmac_f32_e32 v7, v12, v5
	v_sub_f32_e32 v5, v15, v10
	v_add_f32_e32 v5, v8, v5
	v_add_f32_e32 v8, v13, v7
	v_sub_f32_e32 v14, v10, v8
	v_sub_f32_e32 v10, v10, v14
	v_sub_f32_e32 v13, v8, v13
	v_sub_f32_e32 v8, v10, v8
	v_add_f32_e32 v5, v5, v8
	v_sub_f32_e32 v7, v13, v7
	v_add_f32_e32 v5, v7, v5
	v_add_f32_e32 v7, v11, v12
	v_add_f32_e32 v5, v14, v5
	v_sub_f32_e32 v8, v7, v11
	v_mul_f32_e32 v5, v9, v5
	v_sub_f32_e32 v8, v12, v8
	v_add_f32_e32 v5, v8, v5
	v_mul_f32_e32 v11, 0x3f317218, v4
	v_add_f32_e32 v8, v7, v5
	v_fma_f32 v12, v4, s3, -v11
	v_mul_f32_e32 v9, v8, v8
	v_fmac_f32_e32 v12, 0xb102e308, v4
	v_sub_f32_e32 v4, v8, v7
	v_fmamk_f32 v10, v9, 0x3e9b6dac, v168
	v_sub_f32_e32 v4, v5, v4
	v_add_f32_e32 v5, v11, v12
	v_fmaak_f32 v10, v9, v10, 0x3f2aaada
	v_sub_f32_e32 v7, v5, v11
	v_ldexp_f32 v11, v8, 1
	v_mul_f32_e32 v8, v8, v9
	v_mul_f32_e32 v8, v8, v10
	v_add_f32_e32 v9, v11, v8
	v_sub_f32_e32 v10, v9, v11
	v_ldexp_f32 v4, v4, 1
	v_sub_f32_e32 v8, v8, v10
	v_add_f32_e32 v4, v4, v8
	v_add_f32_e32 v8, v9, v4
	v_sub_f32_e32 v9, v8, v9
	v_sub_f32_e32 v4, v4, v9
	v_add_f32_e32 v9, v5, v8
	v_sub_f32_e32 v10, v9, v5
	v_sub_f32_e32 v11, v9, v10
	v_sub_f32_e32 v7, v12, v7
	v_sub_f32_e32 v5, v5, v11
	v_sub_f32_e32 v8, v8, v10
	v_add_f32_e32 v5, v8, v5
	v_add_f32_e32 v8, v7, v4
	v_sub_f32_e32 v10, v8, v7
	v_sub_f32_e32 v11, v8, v10
	v_sub_f32_e32 v7, v7, v11
	v_sub_f32_e32 v4, v4, v10
	v_add_f32_e32 v5, v8, v5
	v_add_f32_e32 v4, v4, v7
	v_add_f32_e32 v7, v9, v5
	v_sub_f32_e32 v8, v7, v9
	v_sub_f32_e32 v5, v5, v8
	v_add_f32_e32 v4, v4, v5
	s_mov_b32 s3, 0x7f800000
	v_add_f32_e32 v4, v7, v4
	v_cmp_neq_f32_e32 vcc, s3, v6
	s_mov_b32 s3, 0x33800000
	v_and_b32_e32 v8, 0xfc0, v32
	v_cndmask_b32_e32 v4, v172, v4, vcc
	v_cmp_lt_f32_e64 vcc, |v6|, s3
	v_lshlrev_b32_e32 v130, 2, v8
	s_nop 0
	v_cndmask_b32_e32 v4, v4, v6, vcc
	v_mul_f32_e32 v4, 0xbfb8aa3b, v4
	v_mul_f32_e32 v4, 0x43800000, v4
	v_exp_f32_e32 v33, v4
	global_load_dwordx2 v[4:5], v3, s[0:1] offset:32
	v_ashrrev_i32_e32 v3, 31, v2
	v_lshlrev_b64 v[6:7], 14, v[2:3]
	v_lshrrev_b32_e32 v3, 4, v1
	v_lshlrev_b32_e32 v2, 4, v2
	v_or_b32_e32 v14, 14, v2
	v_or_b32_e32 v12, 13, v2
	v_or_b32_e32 v8, 12, v2
	v_or_b32_e32 v10, 9, v2
	v_or_b32_e32 v16, 8, v2
	v_or_b32_e32 v18, 7, v2
	v_or_b32_e32 v20, 6, v2
	v_or_b32_e32 v22, 5, v2
	v_or_b32_e32 v24, 4, v2
	v_or_b32_e32 v26, 3, v2
	v_or_b32_e32 v28, 2, v2
	v_or_b32_e32 v30, 1, v2
	v_or_b32_e32 v34, 15, v2
	v_ashrrev_i32_e32 v15, 31, v14
	v_ashrrev_i32_e32 v13, 31, v12
	v_ashrrev_i32_e32 v9, 31, v8
	v_ashrrev_i32_e32 v11, 31, v10
	v_ashrrev_i32_e32 v17, 31, v16
	v_ashrrev_i32_e32 v19, 31, v18
	v_ashrrev_i32_e32 v21, 31, v20
	v_ashrrev_i32_e32 v23, 31, v22
	v_ashrrev_i32_e32 v25, 31, v24
	v_ashrrev_i32_e32 v27, 31, v26
	v_ashrrev_i32_e32 v29, 31, v28
	v_ashrrev_i32_e32 v31, 31, v30
	s_waitcnt vmcnt(0)
	v_lshl_add_u64 v[4:5], v[4:5], 0, v[6:7]
	v_lshl_add_u64 v[4:5], v[4:5], 0, v[130:131]
	v_and_b32_e32 v130, 0xfc, v3
	v_lshl_add_u64 v[4:5], v[4:5], 0, v[130:131]
	global_load_dword v35, v[4:5], off
	v_and_b32_e32 v3, 0x1000, v1
	v_or_b32_e32 v6, 11, v2
	v_or_b32_e32 v4, 10, v2
	v_cmp_ne_u32_e32 vcc, 0, v3
	v_ashrrev_i32_e32 v7, 31, v6
	v_ashrrev_i32_e32 v5, 31, v4
	s_movk_i32 s17, 0x8000
	s_movk_i32 s18, 0xc000
	v_readfirstlane_b32 s3, v1
	s_bitcmp1_b32 s3, 12
	s_cselect_b32 s12, s17, 0x8000
	s_cselect_b32 s13, s18, 0x4000
	s_cselect_b32 s14, 15, 0
	s_cselect_b32 s15, 0x1000, 0
	s_cselect_b32 s16, 0, 15
	v_or_b32_e32 v0, s15, v0
	v_add_u32_e32 v3, s14, v2
	v_lshl_or_b32 v3, v3, 13, v0
	v_lshlrev_b32_e32 v4, 2, v3
	v_lshlrev_b32_e32 v5, 1, v3
	v_readlane_b32 s0, v255, 41
	v_readlane_b32 s1, v255, 42
	v_readlane_b32 s10, v255, 43
	v_readlane_b32 s11, v255, 44
	s_nop 4
	global_load_dword v40, v4, s[0:1]
	v_add_u32_e32 v4, s12, v4
	global_load_dword v41, v4, s[0:1]
	v_add_u32_e32 v4, s12, v4
	global_load_dword v42, v4, s[0:1]
	v_add_u32_e32 v4, s12, v4
	global_load_dword v43, v4, s[0:1]
	v_add_u32_e32 v4, s12, v4
	global_load_dword v44, v4, s[0:1]
	v_add_u32_e32 v4, s12, v4
	global_load_dword v45, v4, s[0:1]
	v_add_u32_e32 v4, s12, v4
	global_load_dword v46, v4, s[0:1]
	v_add_u32_e32 v4, s12, v4
	global_load_dword v47, v4, s[0:1]
	v_add_u32_e32 v4, s12, v4
	global_load_dword v48, v4, s[0:1]
	v_add_u32_e32 v4, s12, v4
	global_load_dword v49, v4, s[0:1]
	v_add_u32_e32 v4, s12, v4
	global_load_dword v50, v4, s[0:1]
	v_add_u32_e32 v4, s12, v4
	global_load_dword v51, v4, s[0:1]
	v_add_u32_e32 v4, s12, v4
	global_load_dword v52, v4, s[0:1]
	v_add_u32_e32 v4, s12, v4
	global_load_dword v53, v4, s[0:1]
	v_add_u32_e32 v4, s12, v4
	global_load_dword v54, v4, s[0:1]
	s_waitcnt vmcnt(15)
	v_cvt_pk_bf16_f32 v6, v35, v35
	global_store_short v5, v6, s[10:11]
	v_add_u32_e32 v5, s13, v5
	s_waitcnt vmcnt(15)
	v_fmac_f32_e32 v40, v33, v35
	v_cvt_pk_bf16_f32 v7, v40, v40
	global_store_short v5, v7, s[10:11]
	v_add_u32_e32 v5, s13, v5
	s_waitcnt vmcnt(15)
	v_fmac_f32_e32 v41, v33, v40
	v_cvt_pk_bf16_f32 v8, v41, v41
	global_store_short v5, v8, s[10:11]
	v_add_u32_e32 v5, s13, v5
	s_waitcnt vmcnt(15)
	v_fmac_f32_e32 v42, v33, v41
	v_cvt_pk_bf16_f32 v9, v42, v42
	global_store_short v5, v9, s[10:11]
	v_add_u32_e32 v5, s13, v5
	s_waitcnt vmcnt(15)
	v_fmac_f32_e32 v43, v33, v42
	v_cvt_pk_bf16_f32 v6, v43, v43
	global_store_short v5, v6, s[10:11]
	v_add_u32_e32 v5, s13, v5
	s_waitcnt vmcnt(15)
	v_fmac_f32_e32 v44, v33, v43
	v_cvt_pk_bf16_f32 v7, v44, v44
	global_store_short v5, v7, s[10:11]
	v_add_u32_e32 v5, s13, v5
	s_waitcnt vmcnt(15)
	v_fmac_f32_e32 v45, v33, v44
	v_cvt_pk_bf16_f32 v8, v45, v45
	global_store_short v5, v8, s[10:11]
	v_add_u32_e32 v5, s13, v5
	s_waitcnt vmcnt(15)
	v_fmac_f32_e32 v46, v33, v45
	v_cvt_pk_bf16_f32 v9, v46, v46
	global_store_short v5, v9, s[10:11]
	v_add_u32_e32 v5, s13, v5
	s_waitcnt vmcnt(15)
	v_fmac_f32_e32 v47, v33, v46
	v_cvt_pk_bf16_f32 v6, v47, v47
	global_store_short v5, v6, s[10:11]
	v_add_u32_e32 v5, s13, v5
	s_waitcnt vmcnt(15)
	v_fmac_f32_e32 v48, v33, v47
	v_cvt_pk_bf16_f32 v7, v48, v48
	global_store_short v5, v7, s[10:11]
	v_add_u32_e32 v5, s13, v5
	s_waitcnt vmcnt(15)
	v_fmac_f32_e32 v49, v33, v48
	v_cvt_pk_bf16_f32 v8, v49, v49
	global_store_short v5, v8, s[10:11]
	v_add_u32_e32 v5, s13, v5
	s_waitcnt vmcnt(15)
	v_fmac_f32_e32 v50, v33, v49
	v_cvt_pk_bf16_f32 v9, v50, v50
	global_store_short v5, v9, s[10:11]
	v_add_u32_e32 v5, s13, v5
	s_waitcnt vmcnt(15)
	v_fmac_f32_e32 v51, v33, v50
	v_cvt_pk_bf16_f32 v6, v51, v51
	global_store_short v5, v6, s[10:11]
	v_add_u32_e32 v5, s13, v5
	s_waitcnt vmcnt(15)
	v_fmac_f32_e32 v52, v33, v51
	v_cvt_pk_bf16_f32 v7, v52, v52
	global_store_short v5, v7, s[10:11]
	v_add_u32_e32 v5, s13, v5
	s_waitcnt vmcnt(15)
	v_fmac_f32_e32 v53, v33, v52
	v_cvt_pk_bf16_f32 v8, v53, v53
	global_store_short v5, v8, s[10:11]
	v_add_u32_e32 v5, s13, v5
	s_waitcnt vmcnt(15)
	v_fmac_f32_e32 v54, v33, v53
	v_mov_b32_e32 v36, v54
	v_add_u32_e32 v2, s16, v2
	s_mov_b64 s[8:9], exec
	s_branch .LBB0_1114
